# phase I idle half round (next layer's weight transposes on workgroups 128..255): the item loader's 16 dependent load pairs issued 16 at a time with counted waits; it no longer outlasts the 9-tile work
# speedup vs baseline: 1.0112x; 1.0071x over previous
; #define LAS __attribute__((address_space(3)))
; __device__ __forceinline__ void transpose_item(const float* W, int K, int N, bf16_t* WT, LAS float* scr, int item, int lane, bool blk = false) {
;     const int nblk = N / 32, kb = item / nblk, nbk = item - kb * nblk, k0 = 64 * kb, n0 = 32 * nbk;
; #pragma unroll 8
;     for (int i = 0; i < 32; ++i) { const int kk = 2 * i + (lane >> 5); scr[kk * 33 + (lane & 31)] = W[(size_t)(k0 + kk) * N + n0 + (lane & 31)]; }
.LBB0_1253:
	s_lshl_b32 s6, s0, 1
	s_lshl_b32 s3, s1, 1
	s_add_i32 s19, s6, 0
	s_add_i32 s18, s3, 0
	v_or_b32_e32 v30, s19, v22
	v_or_b32_e32 v27, s18, v5
	v_or_b32_e32 v19, s19, v6
	v_or_b32_e32 v11, s18, v3
	v_mad_i64_i32 v[30:31], s[18:19], v2, v30, 0
	v_mad_i64_i32 v[28:29], s[18:19], v4, v27, 0
	v_lshl_add_u64 v[30:31], v[30:31], 2, v[20:21]
	v_lshl_add_u64 v[28:29], v[28:29], 2, v[20:21]
	global_load_dword v44, v[30:31], off
	global_load_dword v45, v[28:29], off
	v_mad_u64_u32 v[60:61], s[18:19], v19, s57, v[8:9]
	v_mad_u64_u32 v[62:63], s[18:19], v11, s57, v[8:9]
	s_add_i32 s19, s6, 4
	s_add_i32 s18, s3, 4
	v_or_b32_e32 v30, s19, v22
	v_or_b32_e32 v27, s18, v5
	v_or_b32_e32 v19, s19, v6
	v_or_b32_e32 v11, s18, v3
	v_mad_i64_i32 v[30:31], s[18:19], v2, v30, 0
	v_mad_i64_i32 v[28:29], s[18:19], v4, v27, 0
	v_lshl_add_u64 v[30:31], v[30:31], 2, v[20:21]
	v_lshl_add_u64 v[28:29], v[28:29], 2, v[20:21]
	global_load_dword v46, v[30:31], off
	global_load_dword v47, v[28:29], off
	v_mad_u64_u32 v[64:65], s[18:19], v19, s57, v[8:9]
	v_mad_u64_u32 v[66:67], s[18:19], v11, s57, v[8:9]
	s_add_i32 s19, s6, 8
	s_add_i32 s18, s3, 8
	v_or_b32_e32 v30, s19, v22
	v_or_b32_e32 v27, s18, v5
	v_or_b32_e32 v19, s19, v6
	v_or_b32_e32 v11, s18, v3
	v_mad_i64_i32 v[30:31], s[18:19], v2, v30, 0
	v_mad_i64_i32 v[28:29], s[18:19], v4, v27, 0
	v_lshl_add_u64 v[30:31], v[30:31], 2, v[20:21]
	v_lshl_add_u64 v[28:29], v[28:29], 2, v[20:21]
	global_load_dword v48, v[30:31], off
	global_load_dword v49, v[28:29], off
	v_mad_u64_u32 v[68:69], s[18:19], v19, s57, v[8:9]
	v_mad_u64_u32 v[70:71], s[18:19], v11, s57, v[8:9]
	s_add_i32 s19, s6, 12
	s_add_i32 s18, s3, 12
	v_or_b32_e32 v30, s19, v22
	v_or_b32_e32 v27, s18, v5
	v_or_b32_e32 v19, s19, v6
	v_or_b32_e32 v11, s18, v3
	v_mad_i64_i32 v[30:31], s[18:19], v2, v30, 0
	v_mad_i64_i32 v[28:29], s[18:19], v4, v27, 0
	v_lshl_add_u64 v[30:31], v[30:31], 2, v[20:21]
	v_lshl_add_u64 v[28:29], v[28:29], 2, v[20:21]
	global_load_dword v50, v[30:31], off
	global_load_dword v51, v[28:29], off
	v_mad_u64_u32 v[72:73], s[18:19], v19, s57, v[8:9]
	v_mad_u64_u32 v[74:75], s[18:19], v11, s57, v[8:9]
	s_add_i32 s19, s6, 16
	s_add_i32 s18, s3, 16
	v_or_b32_e32 v30, s19, v22
	v_or_b32_e32 v27, s18, v5
	v_or_b32_e32 v19, s19, v6
	v_or_b32_e32 v11, s18, v3
	v_mad_i64_i32 v[30:31], s[18:19], v2, v30, 0
	v_mad_i64_i32 v[28:29], s[18:19], v4, v27, 0
	v_lshl_add_u64 v[30:31], v[30:31], 2, v[20:21]
	v_lshl_add_u64 v[28:29], v[28:29], 2, v[20:21]
	global_load_dword v52, v[30:31], off
	global_load_dword v53, v[28:29], off
	v_mad_u64_u32 v[76:77], s[18:19], v19, s57, v[8:9]
	v_mad_u64_u32 v[78:79], s[18:19], v11, s57, v[8:9]
	s_add_i32 s19, s6, 20
	s_add_i32 s18, s3, 20
	v_or_b32_e32 v30, s19, v22
	v_or_b32_e32 v27, s18, v5
	v_or_b32_e32 v19, s19, v6
	v_or_b32_e32 v11, s18, v3
	v_mad_i64_i32 v[30:31], s[18:19], v2, v30, 0
	v_mad_i64_i32 v[28:29], s[18:19], v4, v27, 0
	v_lshl_add_u64 v[30:31], v[30:31], 2, v[20:21]
	v_lshl_add_u64 v[28:29], v[28:29], 2, v[20:21]
	global_load_dword v54, v[30:31], off
	global_load_dword v55, v[28:29], off
	v_mad_u64_u32 v[80:81], s[18:19], v19, s57, v[8:9]
	v_mad_u64_u32 v[82:83], s[18:19], v11, s57, v[8:9]
	s_add_i32 s19, s6, 24
	s_add_i32 s18, s3, 24
	v_or_b32_e32 v30, s19, v22
	v_or_b32_e32 v27, s18, v5
	v_or_b32_e32 v19, s19, v6
	v_or_b32_e32 v11, s18, v3
	v_mad_i64_i32 v[30:31], s[18:19], v2, v30, 0
	v_mad_i64_i32 v[28:29], s[18:19], v4, v27, 0
	v_lshl_add_u64 v[30:31], v[30:31], 2, v[20:21]
	v_lshl_add_u64 v[28:29], v[28:29], 2, v[20:21]
	global_load_dword v56, v[30:31], off
	global_load_dword v57, v[28:29], off
	v_mad_u64_u32 v[84:85], s[18:19], v19, s57, v[8:9]
	v_mad_u64_u32 v[86:87], s[18:19], v11, s57, v[8:9]
	s_add_i32 s19, s6, 28
	s_add_i32 s18, s3, 28
	v_or_b32_e32 v30, s19, v22
	v_or_b32_e32 v27, s18, v5
	v_or_b32_e32 v19, s19, v6
	v_or_b32_e32 v11, s18, v3
	v_mad_i64_i32 v[30:31], s[18:19], v2, v30, 0
	v_mad_i64_i32 v[28:29], s[18:19], v4, v27, 0
	v_lshl_add_u64 v[30:31], v[30:31], 2, v[20:21]
	v_lshl_add_u64 v[28:29], v[28:29], 2, v[20:21]
	global_load_dword v58, v[30:31], off
	global_load_dword v59, v[28:29], off
	v_mad_u64_u32 v[88:89], s[18:19], v19, s57, v[8:9]
	v_mad_u64_u32 v[90:91], s[18:19], v11, s57, v[8:9]
	s_add_i32 s0, s0, 16
	s_add_i32 s1, s1, 16
	s_add_i32 s2, s2, -16
	s_waitcnt vmcnt(15)
	ds_write_b32 v60, v44
	s_waitcnt vmcnt(14)
	ds_write_b32 v62, v45
	s_waitcnt vmcnt(13)
	ds_write_b32 v64, v46
	s_waitcnt vmcnt(12)
	ds_write_b32 v66, v47
	s_waitcnt vmcnt(11)
	ds_write_b32 v68, v48
	s_waitcnt vmcnt(10)
	ds_write_b32 v70, v49
	s_waitcnt vmcnt(9)
	ds_write_b32 v72, v50
	s_waitcnt vmcnt(8)
	ds_write_b32 v74, v51
	s_waitcnt vmcnt(7)
	ds_write_b32 v76, v52
	s_waitcnt vmcnt(6)
	ds_write_b32 v78, v53
	s_waitcnt vmcnt(5)
	ds_write_b32 v80, v54
	s_waitcnt vmcnt(4)
	ds_write_b32 v82, v55
	s_waitcnt vmcnt(3)
	ds_write_b32 v84, v56
	s_waitcnt vmcnt(2)
	ds_write_b32 v86, v57
	s_waitcnt vmcnt(1)
	ds_write_b32 v88, v58
	s_waitcnt vmcnt(0)
	ds_write_b32 v90, v59
	s_cmp_lg_u32 s2, 0
	s_cbranch_scc1 .LBB0_1253
; #define LAS __attribute__((address_space(3)))
; __device__ __forceinline__ unsigned pk2(float lo, float hi) { const f32x2 v = {lo, hi}; return __builtin_bit_cast(unsigned, __builtin_convertvector(v, bf16v2_t)); }
; __device__ __forceinline__ void transpose_item(const float* W, int K, int N, bf16_t* WT, LAS float* scr, int item, int lane, bool blk = false) {
;     ...
;     asm volatile("s_waitcnt lgkmcnt(0)" ::: "memory");
;     const int c = lane & 7;
; #pragma unroll
;     for (int j = 0; j < 4; ++j) { const int n = (lane >> 3) + 8 * j; const LAS float* s = scr + (8 * c) * 33 + n;
;         u32x4 o; o.x = pk2(s[0 * 33], s[1 * 33]); o.y = pk2(s[2 * 33], s[3 * 33]); o.z = pk2(s[4 * 33], s[5 * 33]); o.w = pk2(s[6 * 33], s[7 * 33]);
;         *(u32x4*)(blk ? WT + ((size_t)kb * N + (n0 + n)) * 64 + 8 * c : WT + (size_t)(n0 + n) * K + k0 + 8 * c) = o; }
;     asm volatile("s_waitcnt lgkmcnt(0)" ::: "memory");
	s_waitcnt lgkmcnt(0)
	v_ashrrev_i32_e32 v19, 31, v18
	v_lshl_add_u64 v[4:5], v[18:19], 1, v[14:15]
	ds_read2_b32 v[14:15], v23 offset0:33 offset1:41
	ds_read2_b32 v[28:29], v23 offset1:8
	ds_read2_b32 v[30:31], v23 offset0:66 offset1:74
	ds_read2_b32 v[32:33], v23 offset0:99 offset1:107
	ds_read2_b32 v[34:35], v23 offset0:132 offset1:140
	ds_read2_b32 v[36:37], v23 offset0:165 offset1:173
	ds_read2_b32 v[38:39], v23 offset0:198 offset1:206
	ds_read2_b32 v[40:41], v23 offset0:231 offset1:239
	v_mov_b32_e32 v11, v1
	v_or_b32_e32 v2, v16, v9
	v_lshl_add_u64 v[4:5], v[4:5], 0, v[10:11]
	v_mul_lo_u32 v11, v13, v2
	v_mul_lo_u32 v17, v12, v17
	v_mad_u64_u32 v[42:43], s[0:1], v12, v2, 0
	v_add3_u32 v43, v43, v17, v11
	s_waitcnt lgkmcnt(6)
	v_cvt_pk_bf16_f32 v18, v28, v14
	s_waitcnt lgkmcnt(4)
	v_cvt_pk_bf16_f32 v19, v30, v32
	s_waitcnt lgkmcnt(2)
	v_cvt_pk_bf16_f32 v20, v34, v36
	s_waitcnt lgkmcnt(0)
	v_cvt_pk_bf16_f32 v21, v38, v40
	v_lshl_add_u64 v[42:43], v[42:43], 1, v[4:5]
	v_or_b32_e32 v2, v16, v24
	global_store_dwordx4 v[42:43], v[18:21], off
	v_mul_lo_u32 v11, v13, v2
	s_nop 0
	v_cvt_pk_bf16_f32 v18, v29, v15
	v_mad_u64_u32 v[14:15], s[0:1], v12, v2, 0
	v_add3_u32 v15, v15, v17, v11
	v_cvt_pk_bf16_f32 v19, v31, v33
	v_cvt_pk_bf16_f32 v20, v35, v37
	v_cvt_pk_bf16_f32 v21, v39, v41
	v_lshl_add_u64 v[14:15], v[14:15], 1, v[4:5]
	global_store_dwordx4 v[14:15], v[18:21], off
	ds_read2_b32 v[14:15], v23 offset0:16 offset1:24
	ds_read2_b32 v[28:29], v23 offset0:49 offset1:57
	ds_read2_b32 v[30:31], v23 offset0:82 offset1:90
	ds_read2_b32 v[32:33], v23 offset0:115 offset1:123
	ds_read2_b32 v[34:35], v23 offset0:148 offset1:156
	ds_read2_b32 v[36:37], v23 offset0:181 offset1:189
	ds_read2_b32 v[38:39], v23 offset0:214 offset1:222
	ds_read2_b32 v[40:41], v23 offset0:247 offset1:255
	v_or_b32_e32 v2, v16, v25
	v_mul_lo_u32 v11, v13, v2
	v_mad_u64_u32 v[42:43], s[0:1], v12, v2, 0
	v_or_b32_e32 v2, v16, v26
	v_add3_u32 v43, v43, v17, v11
	v_mul_lo_u32 v11, v13, v2
	v_mad_u64_u32 v[12:13], s[0:1], v12, v2, 0
	v_add3_u32 v13, v13, v17, v11
	s_waitcnt lgkmcnt(6)
	v_cvt_pk_bf16_f32 v18, v14, v28
	s_waitcnt lgkmcnt(4)
	v_cvt_pk_bf16_f32 v19, v30, v32
	s_waitcnt lgkmcnt(2)
	v_cvt_pk_bf16_f32 v20, v34, v36
	s_waitcnt lgkmcnt(0)
	v_cvt_pk_bf16_f32 v21, v38, v40
	v_lshl_add_u64 v[42:43], v[42:43], 1, v[4:5]
	v_lshl_add_u64 v[4:5], v[12:13], 1, v[4:5]
	v_cvt_pk_bf16_f32 v12, v15, v29
	v_cvt_pk_bf16_f32 v13, v31, v33
	v_cvt_pk_bf16_f32 v14, v35, v37
	v_cvt_pk_bf16_f32 v15, v39, v41
	global_store_dwordx4 v[42:43], v[18:21], off
	global_store_dwordx4 v[4:5], v[12:15], off
	s_waitcnt lgkmcnt(0)
	s_movk_i32 s0, 0xeff
	v_add_u32_e32 v2, 0x400, v7
	v_cmp_lt_i32_e32 vcc, s0, v7
	s_or_b64 s[54:55], vcc, s[54:55]
	v_mov_b32_e32 v7, v2
	s_andn2_b64 exec, exec, s[54:55]
	s_cbranch_execnz .LBB0_1234
